# k35: k31 + SSD pass-0 x/B/C prep loads on scalar bases (readfirstlane base + s_add per row group, one lane-offset VGPR)
# speedup vs baseline: 1.0046x; 1.0025x over previous
; #define LAS __attribute__((address_space(3)))
; template <int PASS>
; __device__ __forceinline__ void ssd_unit(LAS unsigned char* lds, int ch, int g, const bf16* PROJ, const bf16* XBC, const float* At, const float* DTt, bf16* STS, float* DECS, bf16* OMIX,
;                                          const float* d_skip, const float* ssd_norm) {
;     ...
;         SC[wave * 64 + lane] = v; DL[wave * 64 + lane] = dt;
;         if (lane == (d ? 0 : 63)) TOT[wave] = v;
;     }
;     if (PASS == 0) {
;         { const int n = tid & 63, oct = tid >> 6; const bf16* bp = XBC + (m0 + 8 * oct) * 768 + 512 + 64 * g + n; unsigned vv[8];
; #pragma unroll
;           for (int jj = 0; jj < 8; ++jj) vv[jj] = bp[(size_t)jj * 768];
; #pragma unroll
;           for (int jj = 0; jj < 8; ++jj) asm volatile("" : "+v"(vv[jj]));
;           *(LAS v4u*)(BT + n * RS + oct * 16) = (v4u){vv[0] | (vv[1] << 16), vv[2] | (vv[3] << 16), vv[4] | (vv[5] << 16), vv[6] | (vv[7] << 16)}; }
;         __syncthreads();
;         LAS float* WJ = RED;
;         WJ[tid] = __expf(TOT[tid >> 6] - SC[tid]) * DL[tid];
;         __syncthreads();
;         {
;             const int p = tid & 63, hl = (tid >> 6) & 3, half = tid >> 8; const bf16* xp = XBC + (m0 + 32 * half) * 768 + (4 * g + hl) * 64 + p; float xv[32];
; #pragma unroll
;             for (int jj = 0; jj < 32; ++jj) xv[jj] = bf1(xp[(size_t)jj * 768]);
.LBB0_599:
	s_or_b64 exec, exec, s[4:5]
	s_waitcnt lgkmcnt(0)
	v_lshlrev_b32_e32 v8, 2, v5
	v_lshl_or_b32 v8, s26, 8, v8
	s_and_b64 s[0:1], s[6:7], exec
	v_add_u32_e32 v8, 0, v8
	s_cselect_b32 s0, 63, 0
	v_add_u32_e32 v9, 0x18c00, v8
	v_add_u32_e32 v8, 0x19400, v8
	v_cmp_eq_u32_e32 vcc, s0, v5
	ds_write_b32 v9, v2
	s_waitcnt vmcnt(0)
	ds_write_b32 v8, v7
	s_and_saveexec_b64 s[0:1], vcc
	s_lshl_b32 s3, s26, 2
	s_add_i32 s3, s3, 0
	s_add_i32 s3, s3, 0x19c00
	v_mov_b32_e32 v7, s3
	ds_write_b32 v7, v2
	s_or_b64 exec, exec, s[0:1]
	v_lshlrev_b32_e32 v8, 3, v6
	v_ashrrev_i32_e32 v9, 31, v8
	v_lshl_add_u64 v[8:9], v[8:9], 0, s[42:43]
	v_mov_b64_e32 v[10:11], s[52:53]
	v_mad_u64_u32 v[10:11], s[0:1], v8, s60, v[10:11]
	v_mad_i32_i24 v11, v9, s60, v11
	v_lshlrev_b32_e32 v2, 1, v5
	v_lshl_add_u64 v[8:9], v[10:11], 0, v[2:3]
	s_mov_b64 s[0:1], 0x400
	v_lshl_add_u64 v[10:11], v[8:9], 0, s[0:1]
	global_load_ushort v16, v[8:9], off offset:1024
	global_load_ushort v17, v[8:9], off offset:2560
	global_load_ushort v18, v[10:11], off offset:3072
	v_add_co_u32_e32 v10, vcc, s61, v8
	v_ashrrev_i32_e32 v25, 8, v4
	s_nop 0
	v_addc_co_u32_e32 v11, vcc, 0, v9, vcc
	v_add_co_u32_e32 v8, vcc, s62, v8
	v_lshlrev_b32_e32 v12, 2, v4
	s_nop 0
	v_addc_co_u32_e32 v9, vcc, 0, v9, vcc
	global_load_ushort v19, v[10:11], off offset:1536
	global_load_ushort v20, v[10:11], off offset:3072
	global_load_ushort v21, v[8:9], off offset:512
	global_load_ushort v22, v[8:9], off offset:2048
	global_load_ushort v23, v[8:9], off offset:3584
	v_mul_u32_u24_e32 v8, 0x90, v5
	v_lshlrev_b32_e32 v10, 4, v6
	v_lshl_add_u32 v11, v6, 2, 0
	v_add3_u32 v26, 0, v8, v10
	v_lshlrev_b32_e32 v10, 5, v25
	v_add_u32_e32 v27, 0x19c00, v11
	v_ashrrev_i32_e32 v11, 31, v10
	v_bfe_u32 v24, v4, 6, 2
	v_mov_b64_e32 v[6:7], s[20:21]
	v_lshl_add_u64 v[10:11], v[10:11], 0, s[42:43]
	v_add_u32_e32 v8, 0, v12
	v_add_u32_e32 v28, s64, v12
	v_or_b32_e32 v12, s34, v24
	v_mad_u64_u32 v[6:7], s[0:1], v10, s60, v[6:7]
	v_mov_b32_e32 v9, v3
	v_add_u32_e32 v29, 0x18c00, v8
	v_add_u32_e32 v30, 0x19400, v8
	v_lshlrev_b32_e32 v8, 7, v12
	v_mad_i32_i24 v7, v11, s60, v7
	v_lshl_add_u64 v[6:7], v[6:7], 0, v[8:9]
	v_lshl_add_u64 v[10:11], v[6:7], 0, v[2:3]
	v_mov_b32_e32 v52, v2
	s_nop 0
	v_readfirstlane_b32 s98, v10
	v_readfirstlane_b32 s99, v11
	s_nop 4
	s_movk_i32 s3, 0x6000
	v_lshl_add_u32 v49, v25, 6, 0
	v_lshl_or_b32 v5, v24, 6, v5
	v_mad_u32_u24 v51, v5, s63, v49
	s_waitcnt vmcnt(7)
	s_waitcnt vmcnt(6)
	s_waitcnt vmcnt(5)
	s_waitcnt vmcnt(4)
	v_lshl_or_b32 v6, v17, 16, v16
	s_waitcnt vmcnt(3)
	s_waitcnt vmcnt(2)
	s_waitcnt vmcnt(1)
	s_waitcnt vmcnt(0)
	v_lshl_or_b32 v7, v19, 16, v18
	v_lshl_or_b32 v8, v21, 16, v20
	v_lshl_or_b32 v9, v23, 16, v22
	ds_write_b128 v26, v[6:9] offset:18432
	s_waitcnt lgkmcnt(0)
	s_barrier
	ds_read_b32 v2, v27
	ds_read_b32 v8, v29
	ds_read_b32 v16, v30
	s_waitcnt lgkmcnt(1)
	v_sub_f32_e32 v2, v2, v8
	v_mul_f32_e32 v2, 0x3fb8aa3b, v2
	v_exp_f32_e32 v2, v2
	s_waitcnt lgkmcnt(0)
	v_mul_f32_e32 v2, v16, v2
	ds_write_b32 v28, v2
	s_waitcnt lgkmcnt(0)
	s_barrier
	global_load_ushort v2, v52, s[98:99]
	global_load_ushort v16, v52, s[98:99] offset:1536
	global_load_ushort v18, v52, s[98:99] offset:3072
	s_add_u32 s100, s98, s61
	s_addc_u32 s101, s99, 0
	global_load_ushort v17, v52, s[100:101] offset:512
	global_load_ushort v20, v52, s[100:101] offset:2048
	global_load_ushort v19, v52, s[100:101] offset:3584
	s_add_u32 s90, s98, s62
	s_addc_u32 s91, s99, 0
	global_load_ushort v22, v52, s[90:91] offset:1024
	global_load_ushort v21, v52, s[90:91] offset:2560
	s_add_u32 s4, s98, s65
	s_addc_u32 s5, s99, 0
	global_load_ushort v26, v52, s[4:5]
	global_load_ushort v23, v52, s[4:5] offset:1536
	s_add_u32 s6, s98, s66
	s_addc_u32 s7, s99, 0
	global_load_ushort v27, v52, s[6:7] offset:512
	s_waitcnt vmcnt(7)
	v_lshlrev_b32_e32 v17, 16, v17
	s_waitcnt vmcnt(5)
	v_lshlrev_b32_e32 v19, 16, v19
	global_load_ushort v28, v52, s[4:5] offset:3072
	global_load_ushort v29, v52, s[6:7] offset:3584
	s_add_u32 s8, s98, s67
	s_addc_u32 s9, s99, 0
	global_load_ushort v30, v52, s[8:9] offset:1024
	global_load_ushort v31, v52, s[8:9] offset:2560
	s_add_u32 s100, s98, s3
	s_addc_u32 s101, s99, 0
	global_load_ushort v32, v52, s[100:101]
	global_load_ushort v33, v52, s[100:101] offset:1536
	global_load_ushort v34, v52, s[100:101] offset:3072
	global_load_ushort v35, v52, s[6:7] offset:2048
	v_lshlrev_b32_e32 v15, 16, v16
	s_add_u32 s90, s98, s68
	s_addc_u32 s91, s99, 0
	global_load_ushort v36, v52, s[90:91] offset:512
	global_load_ushort v37, v52, s[90:91] offset:2048
	global_load_ushort v38, v52, s[90:91] offset:3584
	v_lshlrev_b32_e32 v14, 16, v2
	s_add_u32 s4, s98, s69
	s_addc_u32 s5, s99, 0
	global_load_ushort v39, v52, s[4:5] offset:1024
	global_load_ushort v40, v52, s[4:5] offset:2560
	v_lshlrev_b32_e32 v16, 16, v18
	s_add_u32 s6, s98, s70
	s_addc_u32 s7, s99, 0
	global_load_ushort v41, v52, s[6:7]
	global_load_ushort v42, v52, s[6:7] offset:1536
	global_load_ushort v43, v52, s[6:7] offset:3072
	s_add_u32 s8, s98, s71
	s_addc_u32 s9, s99, 0
	global_load_ushort v44, v52, s[8:9] offset:512
	global_load_ushort v45, v52, s[8:9] offset:2048
	global_load_ushort v46, v52, s[8:9] offset:3584
	v_lshlrev_b32_e32 v18, 16, v20
	s_add_u32 s100, s98, s72
	s_addc_u32 s101, s99, 0
	global_load_ushort v47, v52, s[100:101] offset:1024
	global_load_ushort v48, v52, s[100:101] offset:2560
	v_lshlrev_b32_e32 v6, 7, v25
	v_lshlrev_b32_e32 v7, 8, v24
	v_add3_u32 v50, s64, v6, v7
	ds_read_b128 v[6:9], v50
	ds_read_b128 v[10:13], v50 offset:16
	s_waitcnt vmcnt(24)
; #define LAS __attribute__((address_space(3)))
; __device__ __forceinline__ unsigned pk2(float lo, float hi) { const f32x2cv v = {lo, hi}; const bf16x2cv b = __builtin_convertvector(v, bf16x2cv); return __builtin_bit_cast(unsigned, b); }
; template <int PASS>
; __device__ __forceinline__ void ssd_unit(LAS unsigned char* lds, int ch, int g, const bf16* PROJ, const bf16* XBC, const float* At, const float* DTt, bf16* STS, float* DECS, bf16* OMIX,
;                                          const float* d_skip, const float* ssd_norm) {
;     ...
; #pragma unroll
;             for (int d = 0; d < 2; ++d) { const LAS f32x4* wj = (const LAS f32x4*)(WJ + (d * 4 + hl) * 64 + 32 * half);
;                 LAS unsigned char* dst = XT + ((d * 4 + hl) * 64 + p) * RS + half * 64;
; #pragma unroll
;                 for (int o8 = 0; o8 < 4; ++o8) { unsigned pk[4];
;                     const f32x4 wa = wj[2 * o8], wb = wj[2 * o8 + 1];
;                     pk[0] = pk2(xv[8 * o8] * wa.x, xv[8 * o8 + 1] * wa.y); pk[1] = pk2(xv[8 * o8 + 2] * wa.z, xv[8 * o8 + 3] * wa.w); pk[2] = pk2(xv[8 * o8 + 4] * wb.x, xv[8 * o8 + 5] * wb.y); pk[3] = pk2(xv[8 * o8 + 6] * wb.z, xv[8 * o8 + 7] * wb.w);
;                     *(LAS v4u*)(dst + o8 * 16) = (v4u){pk[0], pk[1], pk[2], pk[3]}; } }
;             if (tid < 8) DECS[(size_t)(ch * 2 + (tid >> 2)) * 8 + 4 * g + (tid & 3)] = __expf(TOT[tid]);
	v_lshlrev_b32_e32 v21, 16, v21
	v_lshlrev_b32_e32 v20, 16, v22
	s_waitcnt vmcnt(22)
	v_lshlrev_b32_e32 v23, 16, v23
	s_waitcnt lgkmcnt(1)
	v_pk_mul_f32 v[6:7], v[6:7], v[14:15]
	v_pk_mul_f32 v[8:9], v[8:9], v[16:17]
	s_waitcnt lgkmcnt(0)
	v_pk_mul_f32 v[10:11], v[10:11], v[18:19]
	v_pk_mul_f32 v[12:13], v[12:13], v[20:21]
	v_cvt_pk_bf16_f32 v6, v6, v7
	v_cvt_pk_bf16_f32 v7, v8, v9
	v_cvt_pk_bf16_f32 v8, v10, v11
	v_cvt_pk_bf16_f32 v9, v12, v13
	ds_write_b128 v51, v[6:9] offset:27648
	ds_read_b128 v[6:9], v50 offset:32
	ds_read_b128 v[10:13], v50 offset:48
	v_lshlrev_b32_e32 v22, 16, v26
	s_waitcnt vmcnt(21)
	v_lshlrev_b32_e32 v25, 16, v27
	v_or_b32_e32 v2, 0x100, v5
	s_waitcnt lgkmcnt(1)
	v_pk_mul_f32 v[6:7], v[6:7], v[22:23]
	v_mad_u32_u24 v2, v2, s63, v49
	v_cvt_pk_bf16_f32 v6, v6, v7
	v_cmp_gt_i32_e32 vcc, 8, v4
	s_waitcnt vmcnt(20)
	v_lshlrev_b32_e32 v24, 16, v28
	s_waitcnt vmcnt(19)
	v_lshlrev_b32_e32 v27, 16, v29
	v_pk_mul_f32 v[8:9], v[8:9], v[24:25]
	s_waitcnt vmcnt(17)
	v_lshlrev_b32_e32 v29, 16, v31
	v_lshlrev_b32_e32 v28, 16, v30
	v_cvt_pk_bf16_f32 v7, v8, v9
	s_waitcnt vmcnt(15)
	v_lshlrev_b32_e32 v31, 16, v33
	s_waitcnt vmcnt(13)
	v_lshlrev_b32_e32 v26, 16, v35
	s_waitcnt lgkmcnt(0)
	v_pk_mul_f32 v[10:11], v[10:11], v[26:27]
	v_lshlrev_b32_e32 v30, 16, v32
	v_cvt_pk_bf16_f32 v8, v10, v11
	v_pk_mul_f32 v[10:11], v[12:13], v[28:29]
	s_waitcnt vmcnt(12)
	v_lshlrev_b32_e32 v33, 16, v36
	v_cvt_pk_bf16_f32 v9, v10, v11
	ds_write_b128 v51, v[6:9] offset:27664
	ds_read_b128 v[6:9], v50 offset:64
	ds_read_b128 v[10:13], v50 offset:80
	v_lshlrev_b32_e32 v32, 16, v34
	s_waitcnt vmcnt(10)
	v_lshlrev_b32_e32 v35, 16, v38
	v_lshlrev_b32_e32 v34, 16, v37
	s_waitcnt lgkmcnt(1)
	v_pk_mul_f32 v[6:7], v[6:7], v[30:31]
	v_pk_mul_f32 v[8:9], v[8:9], v[32:33]
	s_waitcnt vmcnt(8)
	v_lshlrev_b32_e32 v37, 16, v40
	v_lshlrev_b32_e32 v36, 16, v39
	v_cvt_pk_bf16_f32 v6, v6, v7
	v_cvt_pk_bf16_f32 v7, v8, v9
	s_waitcnt lgkmcnt(0)
	v_pk_mul_f32 v[8:9], v[10:11], v[34:35]
	v_pk_mul_f32 v[10:11], v[12:13], v[36:37]
	v_cvt_pk_bf16_f32 v8, v8, v9
	v_cvt_pk_bf16_f32 v9, v10, v11
	ds_write_b128 v51, v[6:9] offset:27680
	ds_read_b128 v[6:9], v50 offset:96
	ds_read_b128 v[10:13], v50 offset:112
	s_waitcnt vmcnt(6)
	v_lshlrev_b32_e32 v39, 16, v42
	v_lshlrev_b32_e32 v38, 16, v41
	s_waitcnt vmcnt(4)
	v_lshlrev_b32_e32 v41, 16, v44
	v_lshlrev_b32_e32 v40, 16, v43
	s_waitcnt lgkmcnt(1)
	v_pk_mul_f32 v[6:7], v[6:7], v[38:39]
	v_pk_mul_f32 v[8:9], v[8:9], v[40:41]
	s_waitcnt vmcnt(2)
	v_lshlrev_b32_e32 v43, 16, v46
	v_lshlrev_b32_e32 v42, 16, v45
	s_waitcnt vmcnt(0)
	v_lshlrev_b32_e32 v45, 16, v48
	v_lshlrev_b32_e32 v44, 16, v47
	v_cvt_pk_bf16_f32 v6, v6, v7
	v_cvt_pk_bf16_f32 v7, v8, v9
	s_waitcnt lgkmcnt(0)
	v_pk_mul_f32 v[8:9], v[10:11], v[42:43]
	v_pk_mul_f32 v[10:11], v[12:13], v[44:45]
	v_cvt_pk_bf16_f32 v8, v8, v9
	v_cvt_pk_bf16_f32 v9, v10, v11
	ds_write_b128 v51, v[6:9] offset:27696
	ds_read_b128 v[6:9], v50 offset:1024
	ds_read_b128 v[10:13], v50 offset:1040
	s_waitcnt lgkmcnt(1)
	v_pk_mul_f32 v[6:7], v[6:7], v[14:15]
	v_pk_mul_f32 v[8:9], v[8:9], v[16:17]
	v_cvt_pk_bf16_f32 v6, v6, v7
	v_cvt_pk_bf16_f32 v7, v8, v9
	s_waitcnt lgkmcnt(0)
	v_pk_mul_f32 v[8:9], v[10:11], v[18:19]
	v_pk_mul_f32 v[10:11], v[12:13], v[20:21]
	v_cvt_pk_bf16_f32 v8, v8, v9
	v_cvt_pk_bf16_f32 v9, v10, v11
	ds_write_b128 v2, v[6:9] offset:27648
	ds_read_b128 v[6:9], v50 offset:1056
	ds_read_b128 v[10:13], v50 offset:1072
	s_waitcnt lgkmcnt(1)
	v_pk_mul_f32 v[6:7], v[6:7], v[22:23]
	v_pk_mul_f32 v[8:9], v[8:9], v[24:25]
	v_cvt_pk_bf16_f32 v6, v6, v7
	v_cvt_pk_bf16_f32 v7, v8, v9
	s_waitcnt lgkmcnt(0)
	v_pk_mul_f32 v[8:9], v[10:11], v[26:27]
	v_pk_mul_f32 v[10:11], v[12:13], v[28:29]
	v_cvt_pk_bf16_f32 v8, v8, v9
	v_cvt_pk_bf16_f32 v9, v10, v11
	ds_write_b128 v2, v[6:9] offset:27664
	ds_read_b128 v[6:9], v50 offset:1088
	ds_read_b128 v[10:13], v50 offset:1104
	s_waitcnt lgkmcnt(1)
	v_pk_mul_f32 v[6:7], v[6:7], v[30:31]
	v_pk_mul_f32 v[8:9], v[8:9], v[32:33]
	v_cvt_pk_bf16_f32 v6, v6, v7
	v_cvt_pk_bf16_f32 v7, v8, v9
	s_waitcnt lgkmcnt(0)
	v_pk_mul_f32 v[8:9], v[10:11], v[34:35]
	v_pk_mul_f32 v[10:11], v[12:13], v[36:37]
	v_cvt_pk_bf16_f32 v8, v8, v9
	v_cvt_pk_bf16_f32 v9, v10, v11
	ds_write_b128 v2, v[6:9] offset:27680
	ds_read_b128 v[6:9], v50 offset:1120
	ds_read_b128 v[10:13], v50 offset:1136
	s_waitcnt lgkmcnt(1)
	v_pk_mul_f32 v[6:7], v[6:7], v[38:39]
	v_pk_mul_f32 v[8:9], v[8:9], v[40:41]
	v_cvt_pk_bf16_f32 v6, v6, v7
	v_cvt_pk_bf16_f32 v7, v8, v9
	s_waitcnt lgkmcnt(0)
	v_pk_mul_f32 v[8:9], v[10:11], v[42:43]
	v_pk_mul_f32 v[10:11], v[12:13], v[44:45]
	v_cvt_pk_bf16_f32 v8, v8, v9
	v_cvt_pk_bf16_f32 v9, v10, v11
	ds_write_b128 v2, v[6:9] offset:27696
	s_and_saveexec_b64 s[0:1], vcc
	s_cbranch_execz .LBB0_603
	v_lshl_add_u32 v2, v4, 2, 0
	v_add_u32_e32 v2, 0x19c00, v2
	ds_read_b32 v2, v2
	s_and_b32 s3, s27, -2
	v_ashrrev_i32_e32 v5, 2, v4
	v_add_u32_e32 v6, s3, v5
	v_ashrrev_i32_e32 v7, 31, v6
	s_waitcnt lgkmcnt(0)
	v_mul_f32_e32 v2, 0x3fb8aa3b, v2
	v_exp_f32_e32 v5, v2
	v_and_b32_e32 v2, 3, v4
	v_lshlrev_b64 v[6:7], 5, v[6:7]
	v_lshl_add_u64 v[6:7], s[40:41], 0, v[6:7]
	v_lshlrev_b32_e32 v2, 2, v2
	v_lshl_add_u64 v[6:7], v[6:7], 0, v[2:3]
	s_lshl_b32 s42, s34, 2
	v_lshl_add_u64 v[6:7], v[6:7], 0, s[42:43]
	global_store_dword v[6:7], v5, off
